# candH + P0 x->bf16 row loop: wave sum-of-squares reduction via permlane32/16 swap + DPP row rotates instead of 6 serialized ds_bpermute round trips
# speedup vs baseline: 1.0001x; 1.0001x over previous
; __device__ __forceinline__ float wave_sum(float v) {
; #pragma unroll
;     for (int o = 32; o >= 1; o >>= 1) v += __shfl_xor(v, o);
;     return v;
; }
; __device__ __forceinline__ void p0_prologue(const Args& a, LAS unsigned char* lds) {
;     ...
;         for (; row < MT; row += rstep) {
;             f32x4 vn[4];
;             { const int rn = min(row + rstep, MT - 1); const float* x = rn < NTP ? a.in[0] + (size_t)rn * DM : a.in[1] + (size_t)(rn - NTP) * DM;
; #pragma unroll
;               for (int k = 0; k < 4; ++k) vn[k] = *(const f32x4*)(x + k * 256 + lane * 4); }
;             float ss = 0.f;
; #pragma unroll
;             for (int k = 0; k < 4; ++k) ss += v[k][0] * v[k][0] + v[k][1] * v[k][1] + v[k][2] * v[k][2] + v[k][3] * v[k][3];
;             ss = wave_sum(ss);
;             if (lane == 0) rstd[row] = rsqrtf(ss * (1.0f / DM) + EPS);
.LBB0_42:
	v_add_u32_e32 v51, s10, v42
	v_min_i32_e32 v18, 0x43ff, v51
	v_add_u32_e32 v20, 0xffffc000, v18
	v_cmp_gt_i32_e64 s[4:5], s3, v51
	v_ashrrev_i32_e32 v19, 31, v18
	v_mov_b32_e32 v21, s37
	v_cndmask_b32_e64 v18, v20, v18, s[4:5]
	v_mov_b32_e32 v20, s39
	v_cndmask_b32_e64 v19, 0, v19, s[4:5]
	v_cndmask_b32_e64 v21, v20, v21, s[4:5]
	v_mov_b32_e32 v20, s38
	v_mov_b32_e32 v22, s36
	v_cndmask_b32_e64 v20, v20, v22, s[4:5]
	v_lshlrev_b64 v[18:19], 12, v[18:19]
	v_lshl_add_u64 v[18:19], v[20:21], 0, v[18:19]
	v_lshl_add_u64 v[18:19], v[18:19], 0, v[36:37]
	global_load_dwordx4 v[30:33], v[18:19], off
	global_load_dwordx4 v[26:29], v[18:19], off offset:1024
	global_load_dwordx4 v[22:25], v[18:19], off offset:2048
	s_nop 0
	global_load_dwordx4 v[18:21], v[18:19], off offset:3072
	s_waitcnt vmcnt(7)
	v_mul_f32_e32 v43, v15, v15
	s_waitcnt vmcnt(6)
	v_mul_f32_e32 v52, v11, v11
	v_fmac_f32_e32 v43, v14, v14
	v_fmac_f32_e32 v52, v10, v10
	v_fmac_f32_e32 v43, v16, v16
	v_fmac_f32_e32 v52, v12, v12
	v_fmac_f32_e32 v43, v17, v17
	v_fmac_f32_e32 v52, v13, v13
	v_add_f32_e32 v43, v43, v52
	s_waitcnt vmcnt(5)
	v_mul_f32_e32 v52, v7, v7
	v_fmac_f32_e32 v52, v6, v6
	v_fmac_f32_e32 v52, v8, v8
	v_fmac_f32_e32 v52, v9, v9
	v_add_f32_e32 v43, v52, v43
	s_waitcnt vmcnt(4)
	v_mul_f32_e32 v52, v3, v3
	v_fmac_f32_e32 v52, v2, v2
	v_fmac_f32_e32 v52, v4, v4
	v_fmac_f32_e32 v52, v5, v5
	v_add_f32_e32 v43, v52, v43
	v_mov_b32_e32 v52, v43
	s_nop 1
	v_permlane32_swap_b32_e32 v43, v52
	v_add_f32_e32 v43, v43, v52
	v_mov_b32_e32 v52, v43
	s_nop 1
	v_permlane16_swap_b32_e32 v43, v52
	v_add_f32_e32 v43, v43, v52
	s_nop 1
	v_add_f32_dpp v43, v43, v43 row_ror:8 row_mask:0xf bank_mask:0xf bound_ctrl:1
	s_nop 1
	v_add_f32_dpp v43, v43, v43 row_ror:4 row_mask:0xf bank_mask:0xf bound_ctrl:1
	s_nop 1
	v_add_f32_dpp v43, v43, v43 row_ror:2 row_mask:0xf bank_mask:0xf bound_ctrl:1
	s_nop 1
	v_add_f32_dpp v52, v43, v43 row_ror:1 row_mask:0xf bank_mask:0xf bound_ctrl:1
	v_mov_b32_e32 v53, 0
	s_and_saveexec_b64 s[4:5], vcc
	s_xor_b64 s[4:5], exec, s[4:5]
	v_ashrrev_i32_e32 v43, 31, v42
	s_andn2_saveexec_b64 s[30:31], s[4:5]
	s_cbranch_execz .LBB0_41
	s_waitcnt lgkmcnt(0)
	v_add_f32_e32 v42, v52, v53
	v_fmamk_f32 v42, v42, 0x3a800000, v50
	v_mul_f32_e32 v43, 0x4b800000, v42
	v_cmp_gt_f32_e64 s[4:5], s17, v42
	s_nop 1
	v_cndmask_b32_e64 v42, v42, v43, s[4:5]
	v_rsq_f32_e32 v42, v42
	s_nop 0
	v_mul_f32_e32 v43, 0x45800000, v42
	v_cndmask_b32_e64 v52, v42, v43, s[4:5]
	v_lshl_add_u64 v[42:43], v[34:35], 0, s[28:29]
	global_store_dword v[40:41], v52, off
	s_branch .LBB0_41
